# w_mem_k/v bf16 transposing copies moved from P0 to the 32 side CUs (start of P1, published through a counter polled before memory-K/V GEMM units); side CUs do input-only copies before the sample atten
# speedup vs baseline: 1.1183x; 1.0071x over previous
; #define LAS __attribute__((address_space(3)))
; __device__ __forceinline__ int win_src_col(int np) { const int t = np >> 8, i = np & 255; return (t >= 12 && t < 24) ? ((i < 128) ? 3072 + 128 * (t - 12) + i : 4608 + 128 * (t - 12) + (i - 128)) : np; }
; __device__ __forceinline__ void p0_items(Frame& F, int first, int last, int gw, int NGW) {
;     LAS float* scr = (LAS float*)(F.lds + F.wave * 16640);
;     bf16_t* WIN = WSP(bf16_t, WS_WIN); bf16_t* WKV = WSP(bf16_t, WS_WKV); bf16_t* WOUT = WSP(bf16_t, WS_WOUT); bf16_t* WPW = WSP(bf16_t, WS_WPW); bf16_t* WPOOL = WSP(bf16_t, WS_WPOOL);
;     for (int it = first + gw; it < last; it += NGW) {
;         int r = it; const float* src; bf16_t* dst; int ldw, ldt;
;         if (r < I_IN) { const int kb = r / 152, nb = r % 152; src = F.in[9] + (size_t)(64 * kb) * DIN + win_src_col(64 * nb); ldw = DIN; dst = WIN + (size_t)(64 * nb) * DM + 64 * kb; ldt = DM; }
; __device__ __forceinline__ void p0_prologue(Frame& F, bool all_weights) {
;     const int gw = F.vcu * NWAVES + F.wave, NGW = F.G * NWAVES;
;     p0_items(F, 0, all_weights ? NITEMS : NITEMS_EARLY, gw, NGW);
.LBB0_7:
	s_mov_b64 s[48:49], s[0:1]
	s_ashr_i32 s13, s4, 6
	s_load_dwordx4 s[16:19], s[48:49], 0x0
	s_load_dwordx2 s[44:45], s[48:49], 0x10
	s_load_dwordx8 s[4:11], s[48:49], 0x38
	s_load_dwordx4 s[20:23], s[48:49], 0x58
	s_load_dwordx2 s[42:43], s[48:49], 0xb0
	s_cmpk_lg_i32 s3, 0x100
	s_cselect_b64 s[46:47], -1, 0
	s_lshl_b32 s24, s12, 3
	s_add_i32 s40, s24, s13
	s_lshl_b32 s28, s3, 3
	s_cmpk_eq_i32 s3, 0x100
	s_cselect_b64 s[38:39], -1, 0
	s_movk_i32 s26, 0x2600
	s_and_b64 s[24:25], s[38:39], exec
	v_and_b32_e32 v1, 63, v7
	s_cselect_b32 s29, s26, 0x40d0
	s_cmp_ge_i32 s40, s29
	v_lshlrev_b32_e32 v6, 3, v1
	s_cbranch_scc1 .LBB0_35
	s_waitcnt lgkmcnt(0)
	s_add_u32 s34, s42, 0x20e00000
	s_addc_u32 s35, s43, 0
	s_add_u32 s36, s42, 0x1fe00000
	s_addc_u32 s37, s43, 0
	s_add_u32 s41, s42, 0x100000
	s_addc_u32 s60, s43, 0
	s_add_u32 s61, s42, 0x2100000
	s_addc_u32 s62, s43, 0
	s_load_dwordx4 s[24:27], s[48:49], 0x90
	s_add_u32 s63, s42, 0x2600000
	s_mul_i32 s48, s13, 0x4100
	s_addc_u32 s64, s43, 0
	s_add_i32 s48, s48, 0
	v_lshrrev_b32_e32 v10, 4, v1
	v_and_b32_e32 v4, 15, v7
	v_lshl_add_u32 v9, v4, 4, s48
	v_mul_u32_u24_e32 v35, 0x104, v10
	v_lshrrev_b32_e32 v26, 3, v1
	v_and_b32_e32 v8, 56, v6
	v_lshlrev_b32_e32 v2, 2, v4
	v_mov_b32_e32 v3, 0
	v_mul_u32_u24_e32 v4, 0x104, v8
	v_lshlrev_b32_e32 v5, 2, v26
	v_add_u32_e32 v35, v9, v35
	s_mov_b32 s49, 0
	v_or_b32_e32 v11, 4, v10
	v_or_b32_e32 v12, 8, v10
	v_or_b32_e32 v13, 12, v10
	v_or_b32_e32 v14, 16, v10
	v_or_b32_e32 v15, 20, v10
	v_or_b32_e32 v16, 24, v10
	v_or_b32_e32 v17, 28, v10
	v_or_b32_e32 v18, 32, v10
	v_or_b32_e32 v19, 36, v10
	v_or_b32_e32 v20, 40, v10
	v_or_b32_e32 v21, 44, v10
	v_or_b32_e32 v22, 48, v10
	v_or_b32_e32 v23, 52, v10
	v_or_b32_e32 v24, 56, v10
	v_or_b32_e32 v25, 60, v10
	v_add3_u32 v27, s48, v4, v5
	v_or_b32_e32 v28, 8, v26
	v_or_b32_e32 v29, 16, v26
	v_or_b32_e32 v30, 24, v26
	v_or_b32_e32 v31, 32, v26
	v_or_b32_e32 v32, 40, v26
	v_or_b32_e32 v33, 48, v26
	v_or_b32_e32 v34, 56, v26
	s_lshl_b32 s65, s40, 6
	s_lshl_b32 s66, s3, 9
	s_lshl_b32 s67, s40, 2
	s_lshl_b32 s68, s3, 5
	v_lshlrev_b32_e32 v4, 2, v2
	v_mov_b32_e32 v5, v3
	v_add_u32_e32 v36, 0x410, v35
	v_add_u32_e32 v37, 0x418, v35
	v_add_u32_e32 v38, 0x820, v35
	v_add_u32_e32 v39, 0x828, v35
	v_add_u32_e32 v40, 0xc30, v35
	v_add_u32_e32 v41, 0xc38, v35
	v_add_u32_e32 v42, 0x1040, v35
	v_add_u32_e32 v43, 0x1048, v35
	v_add_u32_e32 v44, 0x1450, v35
	v_add_u32_e32 v45, 0x1458, v35
	v_add_u32_e32 v46, 0x1860, v35
	v_add_u32_e32 v47, 0x1868, v35
	v_add_u32_e32 v48, 0x1c70, v35
	v_add_u32_e32 v49, 0x1c78, v35
	v_add_u32_e32 v50, 0x2080, v35
	v_add_u32_e32 v51, 0x2088, v35
	v_add_u32_e32 v52, 0x2490, v35
	v_add_u32_e32 v53, 0x2498, v35
	v_add_u32_e32 v54, 0x28a0, v35
	v_add_u32_e32 v55, 0x28a8, v35
	v_add_u32_e32 v56, 0x2cb0, v35
	v_add_u32_e32 v57, 0x2cb8, v35
	v_add_u32_e32 v58, 0x30c0, v35
	v_add_u32_e32 v59, 0x30c8, v35
	v_lshlrev_b32_e32 v8, 1, v8
	v_mov_b32_e32 v9, v3
	s_mov_b32 s69, s40
	v_add_u32_e32 v60, 0x34d0, v35
	v_add_u32_e32 v61, 0x34d8, v35
	v_add_u32_e32 v62, 0x38e0, v35
	v_add_u32_e32 v63, 0x38e8, v35
	s_branch .LBB0_11

;     __device__ __forceinline__ bool next(int i, Unit& u) const {
;         int L = i * G + c; if (L >= G1_ALL) return false;
;         u.nt = DM / 64; u.kind = 0;
;         if (L < G1_SPECIAL) { u.pm = MP / 256 + (L >> 3); u.pn = 30 + (L & 7); u.kind = 4; }
;         else if ((L -= G1_SPECIAL) < G1_PROMPT) { int pm, pn; pg8::tile_order(L, MP / 256, G1_NN, pm, pn); u.pm = pm; u.pn = pn; }
;         else if ((L -= G1_PROMPT) < G1_S2) { u.pm = MP / 256 + L / 30; u.pn = L % 30; }
;         else { const int r = L - G1_S2, t = r >> 4, pm = (r >> 2) & 3, pn = r & 3; u.pm = pm; u.pn = pn; u.kind = 1 + t;
;             if (t == 0) { u.A = HM + (size_t)pm * TSTEP4K; u.B = WKV + (size_t)pn * TSTEP4K; }
;             else if (t == 1) { u.A = HM + (size_t)pm * TSTEP4K; u.B = WKV + (size_t)(4 + pn) * TSTEP4K; }
;             else { u.A = WKV + (size_t)(4 + pm) * TSTEP4K; u.B = HM + (size_t)pn * TSTEP4K; }
;             return true; }
.LBB0_136:
	s_add_i32 s12, s12, 1
	s_mul_i32 s5, s12, 0xe0
	s_add_i32 s5, s5, s2
	s_cmpk_lt_i32 s5, 0x53c
	s_cselect_b64 s[56:57], -1, 0
	s_cmpk_gt_i32 s5, 0x53b
	s_cbranch_scc1 .LBB0_156
	s_cmp_gt_i32 s5, 15
	s_cbranch_scc0 .LBB0_152
	s_cmpk_gt_u32 s5, 0x4cf
	s_cbranch_scc0 .LBB0_267
	s_cmpk_gt_u32 s5, 0x50b
	s_mov_b64 s[70:71], -1
	s_cbranch_scc0 .LBB0_268
	s_mov_b32 s99, 0
.Lkv_wait:
	v_mov_b32_e32 v2, 0
	global_load_dword v3, v2, s[48:49] offset:128 sc1
	s_waitcnt vmcnt(0)
	v_readfirstlane_b32 s100, v3
	s_cmp_ge_u32 s100, 32
	s_cbranch_scc1 .Lkv_ready
	s_sleep 16
	s_add_u32 s99, s99, 1
	s_cmp_lt_u32 s99, 0x40000
	s_cbranch_scc1 .Lkv_wait
.Lkv_ready:
	s_add_i32 s59, s5, 0xfffffaf4
	s_lshr_b32 s63, s59, 4
	s_bfe_u32 s58, s59, 0x20002
	s_and_b32 s60, s5, 3
	s_add_i32 s6, s63, 1
	s_cmp_gt_u32 s59, 15
	s_cbranch_scc0 .LBB0_146
	s_lshl_b32 s61, s58, 21
	s_cmp_lg_u32 s63, 1
	s_cbranch_scc0 .LBB0_143
	s_add_u32 s13, s79, s61
	s_addc_u32 s55, s80, 0
	s_add_u32 s54, s13, 0x800000
	s_addc_u32 s55, s55, 0
	s_lshl_b32 s13, s60, 21
	s_add_u32 s64, s75, s13
	s_addc_u32 s65, s76, 0
	s_mov_b64 s[70:71], 0

; __global__ void __launch_bounds__(NTHR, 2) hybrid_fwd(Args args) {
;     ...
;     if ((int)blockIdx.x >= NAS_FREE_FROM && (int)gridDim.x == 256) {
;         Frame F = make_frame(lds);
;         if (F.tid < 64) { unsigned* fl = (unsigned*)(F.ws + WS_CTL) + CW_QREADY; unsigned sp = 0;
;             while (__hip_atomic_load(fl, __ATOMIC_RELAXED, __HIP_MEMORY_SCOPE_AGENT) < (unsigned)G1_SPECIAL) { __builtin_amdgcn_s_sleep(4); if (++sp > (1u << 22)) break; }
;             __builtin_amdgcn_fence(__ATOMIC_ACQUIRE, "agent"); }
;         asm volatile("s_waitcnt vmcnt(0)" ::: "memory"); __syncthreads();
;         for (int u = (int)blockIdx.x - NAS_FREE_FROM; u < NAS_UNITS; u += 256 - NAS_FREE_FROM) attn_sample_head_unit(F, u);
;     }
.LBB0_271:
	s_mov_b32 s98, 1
	s_cmp_gt_i32 s2, 0xdf
	s_cselect_b64 s[4:5], -1, 0
	s_and_b64 s[6:7], s[4:5], s[38:39]
	v_cndmask_b32_e64 v1, 0, 1, s[6:7]
	v_cmp_ne_u32_e64 s[4:5], 1, v1
	s_andn2_b64 vcc, exec, s[6:7]
	s_cbranch_vccnz .LBB0_311
	s_mov_b32 s98, 0
	s_branch .LBB0_311
.Lside_attn:
	v_mov_b32_e32 v2, v0
	s_mov_b64 s[6:7], s[0:1]
	s_load_dwordx4 s[16:19], s[6:7], 0x18
	s_load_dwordx2 s[10:11], s[6:7], 0xb0
	v_readfirstlane_b32 s12, v2
	v_cmp_gt_i32_e32 vcc, 64, v2
	s_and_saveexec_b64 s[6:7], vcc
	s_cbranch_execz .LBB0_282
	s_waitcnt lgkmcnt(0)
	s_add_u32 s8, s10, 0x8000
	s_addc_u32 s9, s11, 0
	s_mov_b32 s13, 0x400001
	v_mov_b32_e32 v1, 0
	s_branch .LBB0_275

; #define LAS __attribute__((address_space(3)))
; __device__ __forceinline__ int win_src_col(int np) { const int t = np >> 8, i = np & 255; return (t >= 12 && t < 24) ? ((i < 128) ? 3072 + 128 * (t - 12) + i : 4608 + 128 * (t - 12) + (i - 128)) : np; }
; __device__ __forceinline__ void p0_items(Frame& F, int first, int last, int gw, int NGW) {
;     LAS float* scr = (LAS float*)(F.lds + F.wave * 16640);
;     bf16_t* WIN = WSP(bf16_t, WS_WIN); bf16_t* WKV = WSP(bf16_t, WS_WKV); bf16_t* WOUT = WSP(bf16_t, WS_WOUT); bf16_t* WPW = WSP(bf16_t, WS_WPW); bf16_t* WPOOL = WSP(bf16_t, WS_WPOOL);
;     for (int it = first + gw; it < last; it += NGW) {
;         int r = it; const float* src; bf16_t* dst; int ldw, ldt;
;         if (r < I_IN) { const int kb = r / 152, nb = r % 152; src = F.in[9] + (size_t)(64 * kb) * DIN + win_src_col(64 * nb); ldw = DIN; dst = WIN + (size_t)(64 * nb) * DM + 64 * kb; ldt = DM; }
; __global__ void __launch_bounds__(NTHR, 2) hybrid_fwd(Args args) {
;     ...
;     {
;         constexpr int NFREE = 256 - NAS_FREE_FROM, N3 = NAS_UNITS - 2 * NFREE, NLATE = NFREE - N3;
;         const int idx = (int)blockIdx.x - NAS_FREE_FROM - N3;
;         if (idx >= 0 && (int)gridDim.x == 256) { Frame F = make_frame(lds);
;             p0_items(F, NITEMS_EARLY, NITEMS, idx * NWAVES + F.wave, NLATE * NWAVES);
;             p0_pool_pad(F, idx * NTHR + F.tid, NLATE * NTHR); p0_pool_frag(F, idx * NTHR + F.tid, NLATE * NTHR); }
;     }
.LBB0_311:
	s_bitcmp1_b32 s98, 1
	s_cbranch_scc1 .Lside_done
	s_cmpk_lt_i32 s2, 0xe0
	s_cselect_b64 s[6:7], -1, 0
	s_xor_b64 s[8:9], s[38:39], -1
	s_or_b64 s[6:7], s[6:7], s[8:9]
	s_and_b64 vcc, exec, s[6:7]
	s_cbranch_vccnz .LBB0_347
	v_mov_b32_e32 v1, v0
	s_mov_b64 s[38:39], s[0:1]
	s_add_i32 s12, s2, 0xffffff20
	v_readfirstlane_b32 s6, v1
	s_ashr_i32 s40, s6, 6
	s_load_dwordx8 s[16:23], s[38:39], 0x48
	s_load_dwordx2 s[6:7], s[38:39], 0xb0
	s_lshl_b32 s8, s12, 3
	s_add_i32 s41, s40, s8
	s_cmpk_gt_i32 s41, 0x12cf
	v_and_b32_e32 v6, 15, v1
	s_cbranch_scc1 .LBB0_340
	s_waitcnt lgkmcnt(0)
	s_add_u32 s13, s6, 0x20e00000
	s_addc_u32 s29, s7, 0
	s_add_u32 s34, s6, 0x1fe00000
	s_addc_u32 s35, s7, 0
	s_add_u32 s36, s6, 0x100000
	s_addc_u32 s37, s7, 0
	s_add_u32 s50, s6, 0x2100000
	s_addc_u32 s51, s7, 0
	s_load_dwordx4 s[8:11], s[38:39], 0x90
	s_add_u32 s52, s6, 0x2600000
	s_mulk_i32 s40, 0x4100
	s_addc_u32 s53, s7, 0
	s_add_i32 s38, s40, 0
	v_bfe_u32 v7, v1, 4, 2
	v_lshlrev_b32_e32 v4, 3, v1
	v_lshl_add_u32 v9, v6, 4, s38
	v_mul_u32_u24_e32 v34, 0x104, v7
	v_bfe_u32 v25, v1, 3, 3
	v_and_b32_e32 v8, 56, v4
	s_add_i32 s54, s41, 0x2600
	v_lshlrev_b32_e32 v2, 2, v6
	v_mov_b32_e32 v3, 0
	v_mul_u32_u24_e32 v4, 0x104, v8
	v_lshlrev_b32_e32 v5, 2, v25
	v_add_u32_e32 v34, v9, v34
	s_mov_b32 s39, 0
	v_or_b32_e32 v10, 4, v7
	v_or_b32_e32 v11, 8, v7
	v_or_b32_e32 v12, 12, v7
	v_or_b32_e32 v13, 16, v7
	v_or_b32_e32 v14, 20, v7
	v_or_b32_e32 v15, 24, v7
	v_or_b32_e32 v16, 28, v7
	v_or_b32_e32 v17, 32, v7
	v_or_b32_e32 v18, 36, v7
	v_or_b32_e32 v19, 40, v7
	v_or_b32_e32 v20, 44, v7
	v_or_b32_e32 v21, 48, v7
	v_or_b32_e32 v22, 52, v7
	v_or_b32_e32 v23, 56, v7
	v_or_b32_e32 v24, 60, v7
	v_add3_u32 v26, s38, v4, v5
	v_or_b32_e32 v27, 8, v25
	v_or_b32_e32 v28, 16, v25
	v_or_b32_e32 v29, 24, v25
	v_or_b32_e32 v30, 32, v25
	v_or_b32_e32 v31, 40, v25
	v_or_b32_e32 v32, 48, v25
	v_or_b32_e32 v33, 56, v25
	s_lshl_b32 s55, s54, 6
	s_lshl_b32 s56, s54, 2
	v_lshlrev_b32_e32 v4, 2, v2
	v_mov_b32_e32 v5, v3
	v_add_u32_e32 v35, 0x410, v34
	v_add_u32_e32 v36, 0x418, v34
	v_add_u32_e32 v37, 0x820, v34
	v_add_u32_e32 v38, 0x828, v34
	v_add_u32_e32 v39, 0xc30, v34
	v_add_u32_e32 v40, 0xc38, v34
	v_add_u32_e32 v41, 0x1040, v34
	v_add_u32_e32 v42, 0x1048, v34
	v_add_u32_e32 v43, 0x1450, v34
	v_add_u32_e32 v44, 0x1458, v34
	v_add_u32_e32 v45, 0x1860, v34
	v_add_u32_e32 v46, 0x1868, v34
	v_add_u32_e32 v47, 0x1c70, v34
	v_add_u32_e32 v48, 0x1c78, v34
	v_add_u32_e32 v49, 0x2080, v34
	v_add_u32_e32 v50, 0x2088, v34
	v_add_u32_e32 v51, 0x2490, v34
	v_add_u32_e32 v52, 0x2498, v34
	v_add_u32_e32 v53, 0x28a0, v34
	v_add_u32_e32 v54, 0x28a8, v34
	v_add_u32_e32 v55, 0x2cb0, v34
	v_add_u32_e32 v56, 0x2cb8, v34
	v_add_u32_e32 v57, 0x30c0, v34
	v_add_u32_e32 v58, 0x30c8, v34
	v_add_u32_e32 v59, 0x34d0, v34
	v_lshlrev_b32_e32 v8, 1, v8
	v_mov_b32_e32 v9, v3
	v_add_u32_e32 v60, 0x34d8, v34
	v_add_u32_e32 v61, 0x38e0, v34
	s_branch .LBB0_316

; __device__ __forceinline__ int win_src_col(int np) { const int t = np >> 8, i = np & 255; return (t >= 12 && t < 24) ? ((i < 128) ? 3072 + 128 * (t - 12) + i : 4608 + 128 * (t - 12) + (i - 128)) : np; }
; __device__ __forceinline__ void p0_items(Frame& F, int first, int last, int gw, int NGW) {
;     ...
;     for (int it = first + gw; it < last; it += NGW) {
;         int r = it; const float* src; bf16_t* dst; int ldw, ldt;
;         if (r < I_IN) { const int kb = r / 152, nb = r % 152; src = F.in[9] + (size_t)(64 * kb) * DIN + win_src_col(64 * nb); ldw = DIN; dst = WIN + (size_t)(64 * nb) * DM + 64 * kb; ldt = DM; }
;         else if ((r -= I_IN) < I_KV) { const int kb = r / 16, nb = r % 16; src = F.in[10] + (size_t)(64 * kb) * DX + 64 * nb; ldw = DX; dst = WKV + (size_t)(64 * nb) * DM + 64 * kb; ldt = DM; }
;         else if ((r -= I_KV) < I_KV) { const int kb = r / 16, nb = r % 16; src = F.in[11] + (size_t)(64 * kb) * DX + 64 * nb; ldw = DX; dst = WKV + (size_t)(1024 + 64 * nb) * DM + 64 * kb; ldt = DM; }
;         else if ((r -= I_KV) < I_OUT) { const int kb = r / 64, nb = r % 64; src = F.in[19] + (size_t)(64 * kb) * DM + 64 * nb; ldw = DM; dst = WOUT + (size_t)(64 * nb) * DM + 64 * kb; ldt = DM; }
;         else if ((r -= I_OUT) < I_PW) { const int kb = r / 24, nb = r % 24; src = F.in[18] + (size_t)(64 * kb) * DCONV + 64 * nb; ldw = DCONV; dst = WPW + (size_t)(64 * nb) * DCONV + 64 * kb; ldt = DCONV; }
;         else { r -= I_PW; const int g = r / I_PL, q = r % I_PL, kb = q / 6, nb = q % 6;
;             src = F.in[12] + (size_t)g * PGRP * PGRP + (size_t)(64 * kb) * PGRP + 64 * nb; ldw = PGRP; dst = WPOOL + (size_t)g * 512 * PGRP + (size_t)(64 * nb) * PGRP + 64 * kb; ldt = PGRP; }
;         p0_transpose_item(src, ldw, dst, ldt, scr, F.lane);
;     }
.LBB0_316:
	s_cmpk_lt_u32 s54, 0x2e00
	s_cbranch_scc1 .Lkv_nopub
	s_bitcmp1_b32 s98, 4
	s_cbranch_scc1 .Lkv_nopub
	s_bitset1_b32 s98, 4
	s_waitcnt vmcnt(0)
	s_barrier
	s_mov_b64 exec, s[14:15]
	s_cbranch_execz .Lkv_pub_done
	buffer_wbl2 sc1
	s_waitcnt vmcnt(0)
	s_add_u32 s100, s6, 0x8080
	s_addc_u32 s101, s7, 0
	v_mov_b32_e32 v3, 0
	v_mov_b32_e32 v2, 1
	global_atomic_add v3, v2, s[100:101]
	s_waitcnt vmcnt(0)
.Lkv_pub_done:
	s_mov_b64 exec, -1

; __global__ void __launch_bounds__(NTHR, 2) hybrid_fwd(Args args) {
;     ...
;     if ((int)blockIdx.x >= NAS_FREE_FROM && (int)gridDim.x == 256) {
;         Frame F = make_frame(lds); states_copy_rows(F, ((int)blockIdx.x - NAS_FREE_FROM) * NWAVES + F.wave, (256 - NAS_FREE_FROM) * NWAVES); }
;     ConvW cw;
.LBB0_355:
	s_and_b32 s99, s98, 3
	s_cmp_lg_u32 s99, 0
	s_cbranch_scc1 .Lside_done
	s_bitset1_b32 s98, 1
	s_branch .Lside_attn

; __global__ void __launch_bounds__(NTHR, 2) hybrid_fwd(Args args) {
	.amdhsa_kernel _Z10hybrid_fwd4Args
		.amdhsa_group_segment_fixed_size 0
		.amdhsa_private_segment_fixed_size 0
		.amdhsa_kernarg_size 440
		.amdhsa_user_sgpr_count 2
		.amdhsa_user_sgpr_dispatch_ptr 0
		.amdhsa_user_sgpr_queue_ptr 0
		.amdhsa_user_sgpr_kernarg_segment_ptr 1
		.amdhsa_user_sgpr_dispatch_id 0
		.amdhsa_user_sgpr_kernarg_preload_length 0
		.amdhsa_user_sgpr_kernarg_preload_offset 0
		.amdhsa_user_sgpr_private_segment_size 0
		.amdhsa_uses_dynamic_stack 0
		.amdhsa_enable_private_segment 0
		.amdhsa_system_sgpr_workgroup_id_x 1
		.amdhsa_system_sgpr_workgroup_id_y 0
		.amdhsa_system_sgpr_workgroup_id_z 0
		.amdhsa_system_sgpr_workgroup_info 0
		.amdhsa_system_vgpr_workitem_id 0
		.amdhsa_next_free_vgpr 256
		.amdhsa_next_free_sgpr 102
		.amdhsa_accum_offset 256
		.amdhsa_reserve_vcc 1
		.amdhsa_float_round_mode_32 0
		.amdhsa_float_round_mode_16_64 0
		.amdhsa_float_denorm_mode_32 3
		.amdhsa_float_denorm_mode_16_64 3
		.amdhsa_dx10_clamp 1
		.amdhsa_ieee_mode 1
		.amdhsa_fp16_overflow 0
		.amdhsa_tg_split 0
		.amdhsa_exception_fp_ieee_invalid_op 0
		.amdhsa_exception_fp_denorm_src 0
		.amdhsa_exception_fp_ieee_div_zero 0
		.amdhsa_exception_fp_ieee_overflow 0
		.amdhsa_exception_fp_ieee_underflow 0
		.amdhsa_exception_fp_ieee_inexact 0
		.amdhsa_exception_int_div_zero 0
	.end_amdhsa_kernel

; __global__ void __launch_bounds__(NTHR, 2) hybrid_fwd(Args args) {
amdhsa.kernels:
  - .agpr_count:     0
    .args:
      - .offset:         0
        .size:           184
        .value_kind:     by_value
      - .offset:         184
        .size:           4
        .value_kind:     hidden_block_count_x
      - .offset:         188
        .size:           4
        .value_kind:     hidden_block_count_y
      - .offset:         192
        .size:           4
        .value_kind:     hidden_block_count_z
      - .offset:         196
        .size:           2
        .value_kind:     hidden_group_size_x
      - .offset:         198
        .size:           2
        .value_kind:     hidden_group_size_y
      - .offset:         200
        .size:           2
        .value_kind:     hidden_group_size_z
      - .offset:         202
        .size:           2
        .value_kind:     hidden_remainder_x
      - .offset:         204
        .size:           2
        .value_kind:     hidden_remainder_y
      - .offset:         206
        .size:           2
        .value_kind:     hidden_remainder_z
      - .offset:         224
        .size:           8
        .value_kind:     hidden_global_offset_x
      - .offset:         232
        .size:           8
        .value_kind:     hidden_global_offset_y
      - .offset:         240
        .size:           8
        .value_kind:     hidden_global_offset_z
      - .offset:         248
        .size:           2
        .value_kind:     hidden_grid_dims
      - .offset:         304
        .size:           4
        .value_kind:     hidden_dynamic_lds_size
    .group_segment_fixed_size: 0
    .kernarg_segment_align: 8
    .kernarg_segment_size: 440
    .language:       OpenCL C
    .language_version:
      - 2
      - 0
    .max_flat_workgroup_size: 512
    .name:           _Z10hybrid_fwd4Args
    .private_segment_fixed_size: 0
    .sgpr_count:     108
    .sgpr_spill_count: 6
    .symbol:         _Z10hybrid_fwd4Args.kd
    .uniform_work_group_size: 1
    .uses_dynamic_stack: false
    .vgpr_count:     256
    .vgpr_spill_count: 0
    .wavefront_size: 64
